# p10 epilogue: hoist 8 rowss loads, drop 7 vmcnt(0) drains
# speedup vs baseline: 1.0135x; 1.0135x over previous
; __device__ __forceinline__ u32x4 pack44(const f32x4 a, const f32x4 b) { u32x4 w; w.x = pk2(a[0], a[1]); w.y = pk2(a[2], a[3]); w.z = pk2(b[0], b[1]); w.w = pk2(b[2], b[3]); return w; }
;     __device__ __forceinline__ bool operator()(f32x4 (&acc)[2][2][4][2], const Unit& u, int wr, int wc, int fr, int fq) const {
;         bf16_t* base = (u.pn < 22) ? a + u.pn * 256 : g + (u.pn - 22) * 256;
;         const int row0 = u.pm * 256 + wr * 64 + fr, cl0 = wc * 32 + 8 * fq; const float* bb = bias2 + (size_t)(row0 >> 12) * (2 * DFF) + u.pn * 256 + cl0;
;         const f32x4 b00 = *(const f32x4*)bb, b01 = *(const f32x4*)(bb + 4), b10 = *(const f32x4*)(bb + 128), b11 = *(const f32x4*)(bb + 132);
; #pragma unroll
;         for (int ai = 0; ai < 2; ++ai)
; #pragma unroll
;             for (int m = 0; m < 4; ++m) { const int row = row0 + ai * 128 + m * 16; const float rstd = rsqrtf(rowss[row] * (1.0f / DM) + EPS);
;                 *(u32x4*)(base + (size_t)row * DFF + cl0) = pack44(acc[ai][0][m][0] * rstd + b00, acc[ai][0][m][1] * rstd + b01);
;                 *(u32x4*)(base + (size_t)row * DFF + cl0 + 128) = pack44(acc[ai][1][m][0] * rstd + b10, acc[ai][1][m][1] * rstd + b11); }
.LBB0_798:
	s_lshl_b32 s0, s0, 8
	s_add_i32 s0, s0, s48
	v_or_b32_e32 v166, s0, v155
	v_ashrrev_i32_e32 v167, 31, v166
	v_lshl_add_u64 v[170:171], v[166:167], 2, s[2:3]
	global_load_dword v167, v[170:171], off
	global_load_dword v236, v[170:171], off offset:64
	global_load_dword v237, v[170:171], off offset:128
	global_load_dword v238, v[170:171], off offset:192
	global_load_dword v239, v[170:171], off offset:512
	global_load_dword v240, v[170:171], off offset:576
	global_load_dword v241, v[170:171], off offset:640
	global_load_dword v242, v[170:171], off offset:704
	s_ashr_i32 s0, s0, 12
	s_mul_hi_i32 s1, s0, 0xb000
	s_mul_i32 s0, s0, 0xb000
	s_add_u32 s6, s46, s0
	s_addc_u32 s15, s47, s1
	s_lshl_b64 s[0:1], s[24:25], 2
	s_add_u32 s0, s6, s0
	v_lshlrev_b32_e32 v130, 2, v158
	s_addc_u32 s1, s15, s1
	global_load_dwordx4 v[142:145], v130, s[0:1]
	global_load_dwordx4 v[138:141], v130, s[0:1] offset:16
	global_load_dwordx4 v[134:137], v130, s[0:1] offset:512
	s_nop 0
	global_load_dwordx4 v[130:133], v130, s[0:1] offset:528
	v_lshlrev_b32_e32 v156, 1, v158
	v_lshl_add_u64 v[168:169], s[26:27], 0, v[156:157]
	v_or_b32_e32 v178, 16, v166
	v_mad_i64_i32 v[176:177], s[0:1], v166, s55, v[168:169]
	v_ashrrev_i32_e32 v179, 31, v178
	v_lshl_add_u64 v[180:181], v[178:179], 2, s[2:3]
	s_waitcnt vmcnt(0)
	v_fmamk_f32 v156, v167, 0x3a000000, v175
	v_mul_f32_e32 v167, 0x4b800000, v156
	v_cmp_gt_f32_e32 vcc, s54, v156
	s_nop 1
	v_cndmask_b32_e32 v156, v156, v167, vcc
	v_rsq_f32_e32 v156, v156
	s_nop 0
	v_mul_f32_e32 v167, 0x45800000, v156
	v_cndmask_b32_e32 v156, v156, v167, vcc
	v_pk_fma_f32 v[128:129], v[128:129], v[156:157], v[144:145] op_sel_hi:[1,0,1]
	v_pk_fma_f32 v[126:127], v[126:127], v[156:157], v[142:143] op_sel_hi:[1,0,1]
	v_pk_fma_f32 v[124:125], v[124:125], v[156:157], v[140:141] op_sel_hi:[1,0,1]
	v_pk_fma_f32 v[122:123], v[122:123], v[156:157], v[138:139] op_sel_hi:[1,0,1]
	v_pk_fma_f32 v[182:183], v[116:117], v[156:157], v[132:133] op_sel_hi:[1,0,1]
	v_pk_fma_f32 v[184:185], v[114:115], v[156:157], v[130:131] op_sel_hi:[1,0,1]
	v_cvt_pk_bf16_f32 v114, v126, v127
	v_cvt_pk_bf16_f32 v115, v128, v129
	v_cvt_pk_bf16_f32 v116, v122, v123
	v_cvt_pk_bf16_f32 v117, v124, v125
	v_pk_fma_f32 v[120:121], v[120:121], v[156:157], v[136:137] op_sel_hi:[1,0,1]
	v_pk_fma_f32 v[118:119], v[118:119], v[156:157], v[134:135] op_sel_hi:[1,0,1]
	global_store_dwordx4 v[176:177], v[114:117], off
	s_nop 1
	v_cvt_pk_bf16_f32 v114, v118, v119
	v_cvt_pk_bf16_f32 v115, v120, v121
	v_cvt_pk_bf16_f32 v116, v184, v185
	v_cvt_pk_bf16_f32 v117, v182, v183
	global_store_dwordx4 v[176:177], v[114:117], off offset:256
	s_nop 0
	s_nop 0
	v_or_b32_e32 v114, 32, v166
	s_nop 0
	v_fmamk_f32 v115, v236, 0x3a000000, v175
	v_mul_f32_e32 v116, 0x4b800000, v115
	v_cmp_gt_f32_e32 vcc, s54, v115
	s_nop 1
	v_cndmask_b32_e32 v115, v115, v116, vcc
	v_rsq_f32_e32 v120, v115
	v_ashrrev_i32_e32 v115, 31, v114
	v_lshl_add_u64 v[118:119], v[114:115], 2, s[2:3]
	v_mad_i64_i32 v[116:117], s[0:1], v178, s55, v[168:169]
	v_mul_f32_e32 v115, 0x45800000, v120
	v_cndmask_b32_e32 v120, v120, v115, vcc
	v_pk_fma_f32 v[112:113], v[112:113], v[120:121], v[144:145] op_sel_hi:[1,0,1]
	v_pk_fma_f32 v[110:111], v[110:111], v[120:121], v[142:143] op_sel_hi:[1,0,1]
	v_pk_fma_f32 v[108:109], v[108:109], v[120:121], v[140:141] op_sel_hi:[1,0,1]
	v_pk_fma_f32 v[106:107], v[106:107], v[120:121], v[138:139] op_sel_hi:[1,0,1]
	v_pk_fma_f32 v[104:105], v[104:105], v[120:121], v[136:137] op_sel_hi:[1,0,1]
	v_pk_fma_f32 v[102:103], v[102:103], v[120:121], v[134:135] op_sel_hi:[1,0,1]
	v_pk_fma_f32 v[122:123], v[100:101], v[120:121], v[132:133] op_sel_hi:[1,0,1]
	v_pk_fma_f32 v[120:121], v[98:99], v[120:121], v[130:131] op_sel_hi:[1,0,1]
	v_cvt_pk_bf16_f32 v98, v110, v111
	v_cvt_pk_bf16_f32 v99, v112, v113
	v_cvt_pk_bf16_f32 v100, v106, v107
	v_cvt_pk_bf16_f32 v101, v108, v109
	global_store_dwordx4 v[116:117], v[98:101], off
	s_nop 1
	v_cvt_pk_bf16_f32 v98, v102, v103
	v_cvt_pk_bf16_f32 v99, v104, v105
	v_cvt_pk_bf16_f32 v100, v120, v121
	v_cvt_pk_bf16_f32 v101, v122, v123
	global_store_dwordx4 v[116:117], v[98:101], off offset:256
	s_nop 0
	s_nop 0
	v_or_b32_e32 v98, 48, v166
	s_nop 0
	v_fmamk_f32 v99, v237, 0x3a000000, v175
	v_mul_f32_e32 v100, 0x4b800000, v99
	v_cmp_gt_f32_e32 vcc, s54, v99
	s_nop 1
	v_cndmask_b32_e32 v99, v99, v100, vcc
	v_rsq_f32_e32 v104, v99
	v_ashrrev_i32_e32 v99, 31, v98
	v_lshl_add_u64 v[102:103], v[98:99], 2, s[2:3]
	v_mad_i64_i32 v[100:101], s[0:1], v114, s55, v[168:169]
	v_mul_f32_e32 v99, 0x45800000, v104
	v_cndmask_b32_e32 v104, v104, v99, vcc
	v_pk_fma_f32 v[96:97], v[96:97], v[104:105], v[144:145] op_sel_hi:[1,0,1]
	v_pk_fma_f32 v[94:95], v[94:95], v[104:105], v[142:143] op_sel_hi:[1,0,1]
	v_pk_fma_f32 v[92:93], v[92:93], v[104:105], v[140:141] op_sel_hi:[1,0,1]
	v_pk_fma_f32 v[90:91], v[90:91], v[104:105], v[138:139] op_sel_hi:[1,0,1]
	v_pk_fma_f32 v[88:89], v[88:89], v[104:105], v[136:137] op_sel_hi:[1,0,1]
	v_pk_fma_f32 v[86:87], v[86:87], v[104:105], v[134:135] op_sel_hi:[1,0,1]
	v_pk_fma_f32 v[106:107], v[84:85], v[104:105], v[132:133] op_sel_hi:[1,0,1]
	v_pk_fma_f32 v[104:105], v[82:83], v[104:105], v[130:131] op_sel_hi:[1,0,1]
	v_cvt_pk_bf16_f32 v82, v94, v95
	v_cvt_pk_bf16_f32 v83, v96, v97
	v_cvt_pk_bf16_f32 v84, v90, v91
	v_cvt_pk_bf16_f32 v85, v92, v93
	global_store_dwordx4 v[100:101], v[82:85], off
	s_nop 1
	v_cvt_pk_bf16_f32 v82, v86, v87
	v_cvt_pk_bf16_f32 v83, v88, v89
	v_cvt_pk_bf16_f32 v84, v104, v105
	v_cvt_pk_bf16_f32 v85, v106, v107
	global_store_dwordx4 v[100:101], v[82:85], off offset:256
	s_nop 0
	s_nop 0
	v_fmamk_f32 v82, v238, 0x3a000000, v175
; __device__ __forceinline__ u32x4 pack44(const f32x4 a, const f32x4 b) { u32x4 w; w.x = pk2(a[0], a[1]); w.y = pk2(a[2], a[3]); w.z = pk2(b[0], b[1]); w.w = pk2(b[2], b[3]); return w; }
;     __device__ __forceinline__ bool operator()(f32x4 (&acc)[2][2][4][2], const Unit& u, int wr, int wc, int fr, int fq) const {
;     ...
;         for (int ai = 0; ai < 2; ++ai)
; #pragma unroll
;             for (int m = 0; m < 4; ++m) { const int row = row0 + ai * 128 + m * 16; const float rstd = rsqrtf(rowss[row] * (1.0f / DM) + EPS);
;                 *(u32x4*)(base + (size_t)row * DFF + cl0) = pack44(acc[ai][0][m][0] * rstd + b00, acc[ai][0][m][1] * rstd + b01);
;                 *(u32x4*)(base + (size_t)row * DFF + cl0 + 128) = pack44(acc[ai][1][m][0] * rstd + b10, acc[ai][1][m][1] * rstd + b11); }
	v_mul_f32_e32 v83, 0x4b800000, v82
	v_cmp_gt_f32_e32 vcc, s54, v82
	s_nop 1
	v_cndmask_b32_e32 v82, v82, v83, vcc
	v_rsq_f32_e32 v84, v82
	v_mad_i64_i32 v[82:83], s[0:1], v98, s55, v[168:169]
	v_mul_f32_e32 v85, 0x45800000, v84
	v_cndmask_b32_e32 v84, v84, v85, vcc
	v_pk_fma_f32 v[80:81], v[80:81], v[84:85], v[144:145] op_sel_hi:[1,0,1]
	v_pk_fma_f32 v[78:79], v[78:79], v[84:85], v[142:143] op_sel_hi:[1,0,1]
	v_pk_fma_f32 v[76:77], v[76:77], v[84:85], v[140:141] op_sel_hi:[1,0,1]
	v_pk_fma_f32 v[74:75], v[74:75], v[84:85], v[138:139] op_sel_hi:[1,0,1]
	v_pk_fma_f32 v[72:73], v[72:73], v[84:85], v[136:137] op_sel_hi:[1,0,1]
	v_pk_fma_f32 v[70:71], v[70:71], v[84:85], v[134:135] op_sel_hi:[1,0,1]
	v_pk_fma_f32 v[86:87], v[68:69], v[84:85], v[132:133] op_sel_hi:[1,0,1]
	v_pk_fma_f32 v[84:85], v[66:67], v[84:85], v[130:131] op_sel_hi:[1,0,1]
	v_cvt_pk_bf16_f32 v66, v78, v79
	v_cvt_pk_bf16_f32 v67, v80, v81
	v_cvt_pk_bf16_f32 v68, v74, v75
	v_cvt_pk_bf16_f32 v69, v76, v77
	global_store_dwordx4 v[82:83], v[66:69], off
	s_nop 1
	v_cvt_pk_bf16_f32 v66, v70, v71
	v_cvt_pk_bf16_f32 v67, v72, v73
	v_cvt_pk_bf16_f32 v68, v84, v85
	v_cvt_pk_bf16_f32 v69, v86, v87
	global_store_dwordx4 v[82:83], v[66:69], off offset:256
	s_nop 0
	s_nop 0
	v_fmamk_f32 v66, v239, 0x3a000000, v175
	v_mul_f32_e32 v67, 0x4b800000, v66
	v_cmp_gt_f32_e32 vcc, s54, v66
	s_nop 1
	v_cndmask_b32_e32 v66, v66, v67, vcc
	v_rsq_f32_e32 v68, v66
	v_add_u32_e32 v66, 0x80, v166
	v_mad_i64_i32 v[66:67], s[0:1], v66, s55, v[168:169]
	v_mul_f32_e32 v69, 0x45800000, v68
	v_cndmask_b32_e32 v68, v68, v69, vcc
	v_pk_fma_f32 v[64:65], v[64:65], v[68:69], v[144:145] op_sel_hi:[1,0,1]
	v_pk_fma_f32 v[62:63], v[62:63], v[68:69], v[142:143] op_sel_hi:[1,0,1]
	v_pk_fma_f32 v[60:61], v[60:61], v[68:69], v[140:141] op_sel_hi:[1,0,1]
	v_pk_fma_f32 v[58:59], v[58:59], v[68:69], v[138:139] op_sel_hi:[1,0,1]
	v_pk_fma_f32 v[56:57], v[56:57], v[68:69], v[136:137] op_sel_hi:[1,0,1]
	v_pk_fma_f32 v[54:55], v[54:55], v[68:69], v[134:135] op_sel_hi:[1,0,1]
	v_pk_fma_f32 v[70:71], v[52:53], v[68:69], v[132:133] op_sel_hi:[1,0,1]
	v_pk_fma_f32 v[68:69], v[50:51], v[68:69], v[130:131] op_sel_hi:[1,0,1]
	v_cvt_pk_bf16_f32 v50, v62, v63
	v_cvt_pk_bf16_f32 v51, v64, v65
	v_cvt_pk_bf16_f32 v52, v58, v59
	v_cvt_pk_bf16_f32 v53, v60, v61
	global_store_dwordx4 v[66:67], v[50:53], off
	s_nop 1
	v_cvt_pk_bf16_f32 v50, v54, v55
	v_cvt_pk_bf16_f32 v51, v56, v57
	v_cvt_pk_bf16_f32 v52, v68, v69
	v_cvt_pk_bf16_f32 v53, v70, v71
	global_store_dwordx4 v[66:67], v[50:53], off offset:256
	s_nop 0
	s_nop 0
	v_fmamk_f32 v50, v240, 0x3a000000, v175
	v_mul_f32_e32 v51, 0x4b800000, v50
	v_cmp_gt_f32_e32 vcc, s54, v50
	s_nop 1
	v_cndmask_b32_e32 v50, v50, v51, vcc
	v_rsq_f32_e32 v52, v50
	v_add_u32_e32 v50, 0x90, v166
	v_mad_i64_i32 v[50:51], s[0:1], v50, s55, v[168:169]
	v_mul_f32_e32 v53, 0x45800000, v52
	v_cndmask_b32_e32 v52, v52, v53, vcc
	v_pk_fma_f32 v[48:49], v[48:49], v[52:53], v[144:145] op_sel_hi:[1,0,1]
	v_pk_fma_f32 v[46:47], v[46:47], v[52:53], v[142:143] op_sel_hi:[1,0,1]
	v_pk_fma_f32 v[44:45], v[44:45], v[52:53], v[140:141] op_sel_hi:[1,0,1]
	v_pk_fma_f32 v[42:43], v[42:43], v[52:53], v[138:139] op_sel_hi:[1,0,1]
	v_pk_fma_f32 v[40:41], v[40:41], v[52:53], v[136:137] op_sel_hi:[1,0,1]
	v_pk_fma_f32 v[38:39], v[38:39], v[52:53], v[134:135] op_sel_hi:[1,0,1]
	v_pk_fma_f32 v[54:55], v[36:37], v[52:53], v[132:133] op_sel_hi:[1,0,1]
	v_pk_fma_f32 v[52:53], v[34:35], v[52:53], v[130:131] op_sel_hi:[1,0,1]
	v_cvt_pk_bf16_f32 v34, v46, v47
	v_cvt_pk_bf16_f32 v35, v48, v49
	v_cvt_pk_bf16_f32 v36, v42, v43
	v_cvt_pk_bf16_f32 v37, v44, v45
	global_store_dwordx4 v[50:51], v[34:37], off
	s_nop 1
	v_cvt_pk_bf16_f32 v34, v38, v39
	v_cvt_pk_bf16_f32 v35, v40, v41
	v_cvt_pk_bf16_f32 v36, v52, v53
	v_cvt_pk_bf16_f32 v37, v54, v55
	global_store_dwordx4 v[50:51], v[34:37], off offset:256
	s_nop 0
	s_nop 0
	v_fmamk_f32 v34, v241, 0x3a000000, v175
	v_mul_f32_e32 v35, 0x4b800000, v34
	v_cmp_gt_f32_e32 vcc, s54, v34
	s_nop 1
	v_cndmask_b32_e32 v34, v34, v35, vcc
	v_rsq_f32_e32 v36, v34
	v_add_u32_e32 v34, 0xa0, v166
	v_mad_i64_i32 v[34:35], s[0:1], v34, s55, v[168:169]
	v_mul_f32_e32 v37, 0x45800000, v36
	v_cndmask_b32_e32 v36, v36, v37, vcc
	v_pk_fma_f32 v[32:33], v[32:33], v[36:37], v[144:145] op_sel_hi:[1,0,1]
	v_pk_fma_f32 v[30:31], v[30:31], v[36:37], v[142:143] op_sel_hi:[1,0,1]
	v_pk_fma_f32 v[28:29], v[28:29], v[36:37], v[140:141] op_sel_hi:[1,0,1]
	v_pk_fma_f32 v[26:27], v[26:27], v[36:37], v[138:139] op_sel_hi:[1,0,1]
	v_pk_fma_f32 v[24:25], v[24:25], v[36:37], v[136:137] op_sel_hi:[1,0,1]
	v_pk_fma_f32 v[22:23], v[22:23], v[36:37], v[134:135] op_sel_hi:[1,0,1]
	v_pk_fma_f32 v[38:39], v[20:21], v[36:37], v[132:133] op_sel_hi:[1,0,1]
	v_pk_fma_f32 v[36:37], v[18:19], v[36:37], v[130:131] op_sel_hi:[1,0,1]
	v_cvt_pk_bf16_f32 v18, v30, v31
	v_cvt_pk_bf16_f32 v19, v32, v33
	v_cvt_pk_bf16_f32 v20, v26, v27
	v_cvt_pk_bf16_f32 v21, v28, v29
	global_store_dwordx4 v[34:35], v[18:21], off
	s_andn2_b64 vcc, exec, s[20:21]
	s_nop 0
	v_cvt_pk_bf16_f32 v18, v22, v23
	v_cvt_pk_bf16_f32 v19, v24, v25
	v_cvt_pk_bf16_f32 v20, v36, v37
	v_cvt_pk_bf16_f32 v21, v38, v39
	global_store_dwordx4 v[34:35], v[18:21], off offset:256
	s_nop 0
	s_nop 0
	v_add_u32_e32 v19, 0xb0, v166
	s_nop 0
	v_fmamk_f32 v18, v242, 0x3a000000, v175
	v_mul_f32_e32 v20, 0x4b800000, v18
	v_cmp_gt_f32_e64 s[0:1], s54, v18
	s_nop 1
	v_cndmask_b32_e64 v18, v18, v20, s[0:1]
	v_rsq_f32_e32 v20, v18
	v_mad_i64_i32 v[18:19], s[24:25], v19, s55, v[168:169]
	v_mul_f32_e32 v21, 0x45800000, v20
	v_cndmask_b32_e64 v20, v20, v21, s[0:1]
	v_pk_fma_f32 v[16:17], v[16:17], v[20:21], v[144:145] op_sel_hi:[1,0,1]
	v_pk_fma_f32 v[14:15], v[14:15], v[20:21], v[142:143] op_sel_hi:[1,0,1]
	v_pk_fma_f32 v[12:13], v[12:13], v[20:21], v[140:141] op_sel_hi:[1,0,1]
	v_pk_fma_f32 v[10:11], v[10:11], v[20:21], v[138:139] op_sel_hi:[1,0,1]
	v_pk_fma_f32 v[8:9], v[8:9], v[20:21], v[136:137] op_sel_hi:[1,0,1]
	v_pk_fma_f32 v[6:7], v[6:7], v[20:21], v[134:135] op_sel_hi:[1,0,1]
	v_pk_fma_f32 v[22:23], v[4:5], v[20:21], v[132:133] op_sel_hi:[1,0,1]
	v_pk_fma_f32 v[20:21], v[2:3], v[20:21], v[130:131] op_sel_hi:[1,0,1]
	v_cvt_pk_bf16_f32 v2, v14, v15
	v_cvt_pk_bf16_f32 v3, v16, v17
	v_cvt_pk_bf16_f32 v4, v10, v11
	v_cvt_pk_bf16_f32 v5, v12, v13
	s_mov_b64 s[0:1], -1
	global_store_dwordx4 v[18:19], v[2:5], off
	s_nop 1
	v_cvt_pk_bf16_f32 v2, v6, v7
	v_cvt_pk_bf16_f32 v3, v8, v9
	v_cvt_pk_bf16_f32 v4, v20, v21
	v_cvt_pk_bf16_f32 v5, v22, v23
	global_store_dwordx4 v[18:19], v[2:5], off offset:256
	s_cbranch_vccnz .LBB0_785
	s_andn2_b64 vcc, exec, s[8:9]
	s_cbranch_vccnz .LBB0_784
	s_barrier
	s_branch .LBB0_784

; __global__ __launch_bounds__(512, 2) void mk_fwd(Params p) {
	.amdhsa_kernel _Z6mk_fwd6Params
		.amdhsa_group_segment_fixed_size 0
		.amdhsa_private_segment_fixed_size 0
		.amdhsa_kernarg_size 480
		.amdhsa_user_sgpr_count 2
		.amdhsa_user_sgpr_dispatch_ptr 0
		.amdhsa_user_sgpr_queue_ptr 0
		.amdhsa_user_sgpr_kernarg_segment_ptr 1
		.amdhsa_user_sgpr_dispatch_id 0
		.amdhsa_user_sgpr_kernarg_preload_length 0
		.amdhsa_user_sgpr_kernarg_preload_offset 0
		.amdhsa_user_sgpr_private_segment_size 0
		.amdhsa_uses_dynamic_stack 0
		.amdhsa_enable_private_segment 0
		.amdhsa_system_sgpr_workgroup_id_x 1
		.amdhsa_system_sgpr_workgroup_id_y 0
		.amdhsa_system_sgpr_workgroup_id_z 0
		.amdhsa_system_sgpr_workgroup_info 0
		.amdhsa_system_vgpr_workitem_id 2
		.amdhsa_next_free_vgpr 244
		.amdhsa_next_free_sgpr 98
		.amdhsa_accum_offset 244
		.amdhsa_reserve_vcc 1
		.amdhsa_float_round_mode_32 0
		.amdhsa_float_round_mode_16_64 0
		.amdhsa_float_denorm_mode_32 3
		.amdhsa_float_denorm_mode_16_64 3
		.amdhsa_dx10_clamp 1
		.amdhsa_ieee_mode 1
		.amdhsa_fp16_overflow 0
		.amdhsa_tg_split 0
		.amdhsa_exception_fp_ieee_invalid_op 0
		.amdhsa_exception_fp_denorm_src 0
		.amdhsa_exception_fp_ieee_div_zero 0
		.amdhsa_exception_fp_ieee_overflow 0
		.amdhsa_exception_fp_ieee_underflow 0
		.amdhsa_exception_fp_ieee_inexact 0
		.amdhsa_exception_int_div_zero 0
	.end_amdhsa_kernel

; __global__ __launch_bounds__(512, 2) void mk_fwd(Params p) {
amdhsa.kernels:
  - .agpr_count:     0
    .args:
      - .offset:         0
        .size:           224
        .value_kind:     by_value
      - .offset:         224
        .size:           4
        .value_kind:     hidden_block_count_x
      - .offset:         228
        .size:           4
        .value_kind:     hidden_block_count_y
      - .offset:         232
        .size:           4
        .value_kind:     hidden_block_count_z
      - .offset:         236
        .size:           2
        .value_kind:     hidden_group_size_x
      - .offset:         238
        .size:           2
        .value_kind:     hidden_group_size_y
      - .offset:         240
        .size:           2
        .value_kind:     hidden_group_size_z
      - .offset:         242
        .size:           2
        .value_kind:     hidden_remainder_x
      - .offset:         244
        .size:           2
        .value_kind:     hidden_remainder_y
      - .offset:         246
        .size:           2
        .value_kind:     hidden_remainder_z
      - .offset:         264
        .size:           8
        .value_kind:     hidden_global_offset_x
      - .offset:         272
        .size:           8
        .value_kind:     hidden_global_offset_y
      - .offset:         280
        .size:           8
        .value_kind:     hidden_global_offset_z
      - .offset:         288
        .size:           2
        .value_kind:     hidden_grid_dims
      - .offset:         312
        .size:           8
        .value_kind:     hidden_multigrid_sync_arg
      - .offset:         344
        .size:           4
        .value_kind:     hidden_dynamic_lds_size
    .group_segment_fixed_size: 0
    .kernarg_segment_align: 8
    .kernarg_segment_size: 480
    .language:       OpenCL C
    .language_version:
      - 2
      - 0
    .max_flat_workgroup_size: 512
    .name:           _Z6mk_fwd6Params
    .private_segment_fixed_size: 0
    .sgpr_count:     104
    .sgpr_spill_count: 94
    .symbol:         _Z6mk_fwd6Params.kd
    .uniform_work_group_size: 1
    .uses_dynamic_stack: false
    .vgpr_count:     244
    .vgpr_spill_count: 0
    .wavefront_size: 64
